# GEMM K-loops: s_setprio removed around MFMA blocks, vmcnt+lgkmcnt waits before each pre-MFMA barrier folded into one s_waitcnt (on v66)
# speedup vs baseline: 1.0083x; 1.0083x over previous
.LBB0_91:
	s_add_u32 s8, s42, 0xfff80080
	s_addc_u32 s9, s43, -1
	s_add_i32 s70, 0, 0x10000
	s_cmp_eq_u32 s69, 28
	s_cselect_b32 vcc_hi, s7, s9
	s_cselect_b32 vcc_lo, s45, s8
	v_add_u32_e32 v1, s70, v169
	s_cselect_b32 s9, s65, s68
	s_cselect_b32 s8, s66, s67
	s_add_i32 s72, 0, 0x14000
	ds_read_b128 v[136:139], v1
	ds_read_b128 v[140:143], v1 offset:1024
	ds_read_b128 v[144:147], v1 offset:2048
	ds_read_b128 v[148:151], v1 offset:3072
	v_add_u32_e32 v1, s72, v169
	ds_read_b128 v[152:155], v1
	ds_read_b128 v[186:189], v1 offset:1024
	ds_read_b128 v[190:193], v1 offset:2048
	ds_read_b128 v[194:197], v1 offset:3072
	v_lshl_add_u64 v[170:171], s[42:43], 0, v[162:163]
	s_add_i32 m0, s97, 0xc000
	ds_read_b128 v[198:201], v214
	ds_read_b128 v[216:219], v214 offset:1024
	ds_read_b128 v[220:223], v214 offset:2048
	ds_read_b128 v[224:227], v214 offset:3072
	ds_read_b128 v[228:231], v214 offset:4096
	ds_read_b128 v[232:235], v214 offset:5120
	ds_read_b128 v[236:239], v214 offset:6144
	ds_read_b128 v[240:243], v214 offset:7168
	global_load_lds_dwordx4 v[170:171], off
	v_lshl_add_u64 v[170:171], s[42:43], 0, v[184:185]
	s_add_i32 m0, s97, 0xe000
	s_nop 0
	global_load_lds_dwordx4 v[170:171], off
	s_waitcnt vmcnt(8) lgkmcnt(0)
	s_barrier
	v_mfma_f32_16x16x32_bf16 v[132:135], v[136:139], v[198:201], v[132:135]
	v_mfma_f32_16x16x32_bf16 v[128:131], v[144:147], v[198:201], v[128:131]
	v_mfma_f32_16x16x32_bf16 v[116:119], v[136:139], v[220:223], v[116:119]
	v_mfma_f32_16x16x32_bf16 v[106:109], v[144:147], v[220:223], v[106:109]
	v_mfma_f32_16x16x32_bf16 v[94:97], v[136:139], v[228:231], v[94:97]
	v_mfma_f32_16x16x32_bf16 v[90:93], v[144:147], v[228:231], v[90:93]
	v_mfma_f32_16x16x32_bf16 v[78:81], v[136:139], v[236:239], v[78:81]
	v_mfma_f32_16x16x32_bf16 v[74:77], v[144:147], v[236:239], v[74:77]
	v_mfma_f32_16x16x32_bf16 v[132:135], v[140:143], v[216:219], v[132:135]
	v_mfma_f32_16x16x32_bf16 v[128:131], v[148:151], v[216:219], v[128:131]
	v_mfma_f32_16x16x32_bf16 v[116:119], v[140:143], v[224:227], v[116:119]
	v_mfma_f32_16x16x32_bf16 v[106:109], v[148:151], v[224:227], v[106:109]
	v_mfma_f32_16x16x32_bf16 v[94:97], v[140:143], v[232:235], v[94:97]
	v_mfma_f32_16x16x32_bf16 v[90:93], v[148:151], v[232:235], v[90:93]
	v_mfma_f32_16x16x32_bf16 v[78:81], v[140:143], v[240:243], v[78:81]
	v_mfma_f32_16x16x32_bf16 v[74:77], v[148:151], v[240:243], v[74:77]
	v_mfma_f32_16x16x32_bf16 v[124:127], v[152:155], v[198:201], v[124:127]
	v_mfma_f32_16x16x32_bf16 v[120:123], v[190:193], v[198:201], v[120:123]
	v_mfma_f32_16x16x32_bf16 v[102:105], v[152:155], v[220:223], v[102:105]
	v_mfma_f32_16x16x32_bf16 v[98:101], v[190:193], v[220:223], v[98:101]
	v_mfma_f32_16x16x32_bf16 v[86:89], v[152:155], v[228:231], v[86:89]
	v_mfma_f32_16x16x32_bf16 v[82:85], v[190:193], v[228:231], v[82:85]
	v_mfma_f32_16x16x32_bf16 v[70:73], v[152:155], v[236:239], v[70:73]
	v_mfma_f32_16x16x32_bf16 v[66:69], v[190:193], v[236:239], v[66:69]
	v_mfma_f32_16x16x32_bf16 v[124:127], v[186:189], v[216:219], v[124:127]
	v_mfma_f32_16x16x32_bf16 v[120:123], v[194:197], v[216:219], v[120:123]
	v_mfma_f32_16x16x32_bf16 v[102:105], v[186:189], v[224:227], v[102:105]
	v_mfma_f32_16x16x32_bf16 v[98:101], v[194:197], v[224:227], v[98:101]
	v_mfma_f32_16x16x32_bf16 v[86:89], v[186:189], v[232:235], v[86:89]
	v_mfma_f32_16x16x32_bf16 v[82:85], v[194:197], v[232:235], v[82:85]
	v_mfma_f32_16x16x32_bf16 v[70:73], v[186:189], v[240:243], v[70:73]
	v_mfma_f32_16x16x32_bf16 v[66:69], v[194:197], v[240:243], v[66:69]
	s_barrier
	s_add_i32 s70, s70, s57
	v_lshl_add_u64 v[170:171], s[8:9], 0, v[156:157]
	s_mov_b32 m0, s70
	ds_read_b128 v[198:201], v214 offset:16384
	ds_read_b128 v[216:219], v214 offset:17408
	ds_read_b128 v[220:223], v214 offset:18432
	ds_read_b128 v[224:227], v214 offset:19456
	ds_read_b128 v[228:231], v214 offset:20480
	ds_read_b128 v[232:235], v214 offset:21504
	ds_read_b128 v[236:239], v214 offset:22528
	ds_read_b128 v[240:243], v214 offset:23552
	global_load_lds_dwordx4 v[170:171], off
	s_add_i32 m0, s70, 0x2000
	s_add_u32 s70, s8, 0x80000
	v_lshl_add_u64 v[172:173], s[8:9], 0, v[160:161]
	s_addc_u32 s71, s9, 0
	s_add_i32 s72, s72, s57
	global_load_lds_dwordx4 v[172:173], off
	v_lshl_add_u64 v[244:245], s[70:71], 0, v[156:157]
	s_mov_b32 m0, s72
	v_lshl_add_u64 v[246:247], vcc, 0, v[158:159]
	global_load_lds_dwordx4 v[244:245], off
	v_lshl_add_u64 v[244:245], s[70:71], 0, v[160:161]
	s_add_i32 m0, s72, 0x2000
	s_nop 0
	global_load_lds_dwordx4 v[244:245], off
	v_lshl_add_u64 v[244:245], vcc, 0, v[110:111]
	s_mov_b32 m0, s97
	s_nop 0
	global_load_lds_dwordx4 v[244:245], off
	s_mov_b32 m0, s35
	s_nop 0
	global_load_lds_dwordx4 v[246:247], off
	s_waitcnt vmcnt(8) lgkmcnt(0)
	s_barrier
	v_mfma_f32_16x16x32_bf16 v[62:65], v[136:139], v[198:201], v[62:65]
	v_mfma_f32_16x16x32_bf16 v[58:61], v[144:147], v[198:201], v[58:61]
	v_mfma_f32_16x16x32_bf16 v[46:49], v[136:139], v[220:223], v[46:49]
	v_mfma_f32_16x16x32_bf16 v[42:45], v[144:147], v[220:223], v[42:45]
	v_mfma_f32_16x16x32_bf16 v[30:33], v[136:139], v[228:231], v[30:33]
	v_mfma_f32_16x16x32_bf16 v[26:29], v[144:147], v[228:231], v[26:29]
	v_mfma_f32_16x16x32_bf16 v[14:17], v[136:139], v[236:239], v[14:17]
	v_mfma_f32_16x16x32_bf16 v[10:13], v[144:147], v[236:239], v[10:13]
	v_mfma_f32_16x16x32_bf16 v[62:65], v[140:143], v[216:219], v[62:65]
	v_mfma_f32_16x16x32_bf16 v[58:61], v[148:151], v[216:219], v[58:61]
	v_mfma_f32_16x16x32_bf16 v[46:49], v[140:143], v[224:227], v[46:49]
	v_mfma_f32_16x16x32_bf16 v[42:45], v[148:151], v[224:227], v[42:45]
	v_mfma_f32_16x16x32_bf16 v[30:33], v[140:143], v[232:235], v[30:33]
	v_mfma_f32_16x16x32_bf16 v[26:29], v[148:151], v[232:235], v[26:29]
	v_mfma_f32_16x16x32_bf16 v[14:17], v[140:143], v[240:243], v[14:17]
	v_mfma_f32_16x16x32_bf16 v[10:13], v[148:151], v[240:243], v[10:13]
	v_mfma_f32_16x16x32_bf16 v[54:57], v[152:155], v[198:201], v[54:57]
	v_mfma_f32_16x16x32_bf16 v[50:53], v[190:193], v[198:201], v[50:53]
	v_mfma_f32_16x16x32_bf16 v[38:41], v[152:155], v[220:223], v[38:41]
	v_mfma_f32_16x16x32_bf16 v[34:37], v[190:193], v[220:223], v[34:37]
	v_mfma_f32_16x16x32_bf16 v[22:25], v[152:155], v[228:231], v[22:25]
	v_mfma_f32_16x16x32_bf16 v[18:21], v[190:193], v[228:231], v[18:21]
	v_mfma_f32_16x16x32_bf16 v[6:9], v[152:155], v[236:239], v[6:9]
	v_mfma_f32_16x16x32_bf16 v[2:5], v[190:193], v[236:239], v[2:5]
	v_mfma_f32_16x16x32_bf16 v[54:57], v[186:189], v[216:219], v[54:57]
	v_mfma_f32_16x16x32_bf16 v[50:53], v[194:197], v[216:219], v[50:53]
	v_mfma_f32_16x16x32_bf16 v[38:41], v[186:189], v[224:227], v[38:41]
	v_mfma_f32_16x16x32_bf16 v[34:37], v[194:197], v[224:227], v[34:37]
	v_mfma_f32_16x16x32_bf16 v[22:25], v[186:189], v[232:235], v[22:25]
	v_mfma_f32_16x16x32_bf16 v[18:21], v[194:197], v[232:235], v[18:21]
	v_mfma_f32_16x16x32_bf16 v[6:9], v[186:189], v[240:243], v[6:9]
	v_mfma_f32_16x16x32_bf16 v[2:5], v[194:197], v[240:243], v[2:5]
	s_barrier
	s_add_i32 s72, 0, 0x18000
	v_add_u32_e32 v1, s72, v169
	s_add_i32 s73, 0, 0x1c000
	ds_read_b128 v[136:139], v1
	ds_read_b128 v[140:143], v1 offset:1024
	ds_read_b128 v[144:147], v1 offset:2048
	ds_read_b128 v[148:151], v1 offset:3072
	v_add_u32_e32 v1, s73, v169
	ds_read_b128 v[152:155], v1
	ds_read_b128 v[186:189], v1 offset:1024
	ds_read_b128 v[190:193], v1 offset:2048
	ds_read_b128 v[194:197], v1 offset:3072
	s_add_u32 s70, vcc_lo, 0x80000
	s_addc_u32 s71, vcc_hi, 0
	s_mov_b32 m0, s55
	v_lshl_add_u64 v[248:249], s[70:71], 0, v[110:111]
	ds_read_b128 v[198:201], v214 offset:32768
	ds_read_b128 v[216:219], v214 offset:33792
	ds_read_b128 v[220:223], v214 offset:34816
	ds_read_b128 v[224:227], v214 offset:35840
	ds_read_b128 v[228:231], v214 offset:36864
	ds_read_b128 v[232:235], v214 offset:37888
	ds_read_b128 v[236:239], v214 offset:38912
	ds_read_b128 v[240:243], v214 offset:39936
	global_load_lds_dwordx4 v[248:249], off
	v_lshl_add_u64 v[248:249], s[70:71], 0, v[158:159]
	s_mov_b32 m0, s34
	s_nop 0
	global_load_lds_dwordx4 v[248:249], off
	s_waitcnt vmcnt(8) lgkmcnt(0)
	s_barrier
	v_mfma_f32_16x16x32_bf16 v[132:135], v[136:139], v[198:201], v[132:135]
	v_mfma_f32_16x16x32_bf16 v[128:131], v[144:147], v[198:201], v[128:131]
	v_mfma_f32_16x16x32_bf16 v[116:119], v[136:139], v[220:223], v[116:119]
	v_mfma_f32_16x16x32_bf16 v[106:109], v[144:147], v[220:223], v[106:109]
	v_mfma_f32_16x16x32_bf16 v[94:97], v[136:139], v[228:231], v[94:97]
	v_mfma_f32_16x16x32_bf16 v[90:93], v[144:147], v[228:231], v[90:93]
	v_mfma_f32_16x16x32_bf16 v[78:81], v[136:139], v[236:239], v[78:81]
	v_mfma_f32_16x16x32_bf16 v[74:77], v[144:147], v[236:239], v[74:77]
	v_mfma_f32_16x16x32_bf16 v[132:135], v[140:143], v[216:219], v[132:135]
	v_mfma_f32_16x16x32_bf16 v[128:131], v[148:151], v[216:219], v[128:131]
	v_mfma_f32_16x16x32_bf16 v[116:119], v[140:143], v[224:227], v[116:119]
	v_mfma_f32_16x16x32_bf16 v[106:109], v[148:151], v[224:227], v[106:109]
	v_mfma_f32_16x16x32_bf16 v[94:97], v[140:143], v[232:235], v[94:97]
	v_mfma_f32_16x16x32_bf16 v[90:93], v[148:151], v[232:235], v[90:93]
	v_mfma_f32_16x16x32_bf16 v[78:81], v[140:143], v[240:243], v[78:81]
	v_mfma_f32_16x16x32_bf16 v[74:77], v[148:151], v[240:243], v[74:77]
	v_mfma_f32_16x16x32_bf16 v[124:127], v[152:155], v[198:201], v[124:127]
	v_mfma_f32_16x16x32_bf16 v[120:123], v[190:193], v[198:201], v[120:123]
	v_mfma_f32_16x16x32_bf16 v[102:105], v[152:155], v[220:223], v[102:105]
	v_mfma_f32_16x16x32_bf16 v[98:101], v[190:193], v[220:223], v[98:101]
	v_mfma_f32_16x16x32_bf16 v[86:89], v[152:155], v[228:231], v[86:89]
	v_mfma_f32_16x16x32_bf16 v[82:85], v[190:193], v[228:231], v[82:85]
	v_mfma_f32_16x16x32_bf16 v[70:73], v[152:155], v[236:239], v[70:73]
	v_mfma_f32_16x16x32_bf16 v[66:69], v[190:193], v[236:239], v[66:69]
	v_mfma_f32_16x16x32_bf16 v[124:127], v[186:189], v[216:219], v[124:127]
	v_mfma_f32_16x16x32_bf16 v[120:123], v[194:197], v[216:219], v[120:123]
	v_mfma_f32_16x16x32_bf16 v[102:105], v[186:189], v[224:227], v[102:105]
	v_mfma_f32_16x16x32_bf16 v[98:101], v[194:197], v[224:227], v[98:101]
	v_mfma_f32_16x16x32_bf16 v[86:89], v[186:189], v[232:235], v[86:89]
	v_mfma_f32_16x16x32_bf16 v[82:85], v[194:197], v[232:235], v[82:85]
	v_mfma_f32_16x16x32_bf16 v[70:73], v[186:189], v[240:243], v[70:73]
	v_mfma_f32_16x16x32_bf16 v[66:69], v[194:197], v[240:243], v[66:69]
	s_barrier
	s_add_i32 s70, s72, s57
	v_lshl_add_u64 v[170:171], v[170:171], 0, s[26:27]
	s_mov_b32 m0, s70
	ds_read_b128 v[198:201], v214 offset:49152
	ds_read_b128 v[216:219], v214 offset:50176
	ds_read_b128 v[220:223], v214 offset:51200
	ds_read_b128 v[224:227], v214 offset:52224
	ds_read_b128 v[228:231], v214 offset:53248
	ds_read_b128 v[232:235], v214 offset:54272
	ds_read_b128 v[236:239], v214 offset:55296
	ds_read_b128 v[240:243], v214 offset:56320
	global_load_lds_dwordx4 v[170:171], off
	s_add_i32 m0, s70, 0x2000
	s_add_u32 s8, s8, 0x80080
	v_lshl_add_u64 v[170:171], v[172:173], 0, s[26:27]
	s_addc_u32 s9, s9, 0
	s_add_i32 s70, s73, s57
	global_load_lds_dwordx4 v[170:171], off
	v_lshl_add_u64 v[170:171], s[8:9], 0, v[156:157]
	s_mov_b32 m0, s70
	s_nop 0
	global_load_lds_dwordx4 v[170:171], off
	v_lshl_add_u64 v[170:171], s[8:9], 0, v[160:161]
	s_add_i32 m0, s70, 0x2000
	s_nop 0
	global_load_lds_dwordx4 v[170:171], off
	v_lshl_add_u64 v[170:171], v[244:245], 0, s[26:27]
	s_mov_b32 m0, s60
	s_nop 0
	global_load_lds_dwordx4 v[170:171], off
	v_lshl_add_u64 v[170:171], v[246:247], 0, s[26:27]
	s_mov_b32 m0, s61
	s_nop 0
	global_load_lds_dwordx4 v[170:171], off
	s_waitcnt vmcnt(8) lgkmcnt(0)
	s_barrier
	v_mfma_f32_16x16x32_bf16 v[62:65], v[136:139], v[198:201], v[62:65]
	v_mfma_f32_16x16x32_bf16 v[58:61], v[144:147], v[198:201], v[58:61]
	v_mfma_f32_16x16x32_bf16 v[46:49], v[136:139], v[220:223], v[46:49]
	v_mfma_f32_16x16x32_bf16 v[42:45], v[144:147], v[220:223], v[42:45]
	v_mfma_f32_16x16x32_bf16 v[30:33], v[136:139], v[228:231], v[30:33]
	v_mfma_f32_16x16x32_bf16 v[26:29], v[144:147], v[228:231], v[26:29]
	v_mfma_f32_16x16x32_bf16 v[14:17], v[136:139], v[236:239], v[14:17]
	v_mfma_f32_16x16x32_bf16 v[10:13], v[144:147], v[236:239], v[10:13]
	v_mfma_f32_16x16x32_bf16 v[62:65], v[140:143], v[216:219], v[62:65]
	v_mfma_f32_16x16x32_bf16 v[58:61], v[148:151], v[216:219], v[58:61]
	v_mfma_f32_16x16x32_bf16 v[46:49], v[140:143], v[224:227], v[46:49]
	v_mfma_f32_16x16x32_bf16 v[42:45], v[148:151], v[224:227], v[42:45]
	v_mfma_f32_16x16x32_bf16 v[30:33], v[140:143], v[232:235], v[30:33]
	v_mfma_f32_16x16x32_bf16 v[26:29], v[148:151], v[232:235], v[26:29]
	v_mfma_f32_16x16x32_bf16 v[14:17], v[140:143], v[240:243], v[14:17]
	v_mfma_f32_16x16x32_bf16 v[10:13], v[148:151], v[240:243], v[10:13]
	v_mfma_f32_16x16x32_bf16 v[54:57], v[152:155], v[198:201], v[54:57]
	v_mfma_f32_16x16x32_bf16 v[50:53], v[190:193], v[198:201], v[50:53]
	v_mfma_f32_16x16x32_bf16 v[38:41], v[152:155], v[220:223], v[38:41]
	v_mfma_f32_16x16x32_bf16 v[34:37], v[190:193], v[220:223], v[34:37]
	v_mfma_f32_16x16x32_bf16 v[22:25], v[152:155], v[228:231], v[22:25]
	v_mfma_f32_16x16x32_bf16 v[18:21], v[190:193], v[228:231], v[18:21]
	v_mfma_f32_16x16x32_bf16 v[6:9], v[152:155], v[236:239], v[6:9]
	v_mfma_f32_16x16x32_bf16 v[2:5], v[190:193], v[236:239], v[2:5]
	v_mfma_f32_16x16x32_bf16 v[54:57], v[186:189], v[216:219], v[54:57]
	v_mfma_f32_16x16x32_bf16 v[50:53], v[194:197], v[216:219], v[50:53]
	v_mfma_f32_16x16x32_bf16 v[38:41], v[186:189], v[224:227], v[38:41]
	v_mfma_f32_16x16x32_bf16 v[34:37], v[194:197], v[224:227], v[34:37]
	v_mfma_f32_16x16x32_bf16 v[22:25], v[186:189], v[232:235], v[22:25]
	v_mfma_f32_16x16x32_bf16 v[18:21], v[194:197], v[232:235], v[18:21]
	v_mfma_f32_16x16x32_bf16 v[6:9], v[186:189], v[240:243], v[6:9]
	v_mfma_f32_16x16x32_bf16 v[2:5], v[194:197], v[240:243], v[2:5]
	s_barrier
	s_add_i32 s69, s69, 2
	s_add_u32 s42, s42, 0x100
	s_addc_u32 s43, s43, 0
	s_add_u32 s67, s67, 0x100
	s_addc_u32 s68, s68, 0
	s_cmp_gt_u32 s69, 29
	s_cbranch_scc0 .LBB0_91
	s_and_b64 vcc, exec, s[16:17]
	s_cbranch_vccz .LBB0_94
	s_barrier

.LBB0_553:
	s_add_i32 s72, s8, 2
	s_add_u32 s9, s92, 0xfff80080
	s_addc_u32 s73, s93, -1
	s_add_i32 s74, 0, 0x10000
	s_cmp_eq_u32 s69, s8
	s_cselect_b32 s95, s7, s73
	s_cselect_b32 s94, s49, s9
	v_add_u32_e32 v154, s74, v1
	s_cselect_b32 s9, s47, s71
	s_cselect_b32 s8, s68, s70
	s_add_i32 s73, 0, 0x14000
	s_waitcnt lgkmcnt(0)
	ds_read_b128 v[150:153], v154
	ds_read_b128 v[158:161], v154 offset:1024
	ds_read_b128 v[184:187], v154 offset:2048
	ds_read_b128 v[188:191], v154 offset:3072
	v_add_u32_e32 v154, s73, v1
	ds_read_b128 v[192:195], v154
	ds_read_b128 v[196:199], v154 offset:1024
	ds_read_b128 v[214:217], v154 offset:2048
	ds_read_b128 v[218:221], v154 offset:3072
	v_lshl_add_u64 v[154:155], s[92:93], 0, v[146:147]
	s_add_i32 m0, s17, 0xc000
	ds_read_b128 v[222:225], v156
	ds_read_b128 v[226:229], v156 offset:1024
	ds_read_b128 v[230:233], v156 offset:2048
	ds_read_b128 v[234:237], v156 offset:3072
	ds_read_b128 v[238:241], v156 offset:4096
	ds_read_b128 v[242:245], v156 offset:5120
	ds_read_b128 v[246:249], v156 offset:6144
	ds_read_b128 v[170:173], v156 offset:7168
	global_load_lds_dwordx4 v[154:155], off
	v_lshl_add_u64 v[154:155], s[92:93], 0, v[148:149]
	s_add_i32 m0, s17, 0xe000
	s_nop 0
	global_load_lds_dwordx4 v[154:155], off
	s_waitcnt vmcnt(8) lgkmcnt(0)
	s_barrier
	v_mfma_f32_16x16x32_bf16 v[132:135], v[150:153], v[222:225], v[132:135]
	v_mfma_f32_16x16x32_bf16 v[128:131], v[184:187], v[222:225], v[128:131]
	v_mfma_f32_16x16x32_bf16 v[124:127], v[150:153], v[230:233], v[124:127]
	v_mfma_f32_16x16x32_bf16 v[120:123], v[184:187], v[230:233], v[120:123]
	v_mfma_f32_16x16x32_bf16 v[106:109], v[150:153], v[238:241], v[106:109]
	v_mfma_f32_16x16x32_bf16 v[98:101], v[184:187], v[238:241], v[98:101]
	v_mfma_f32_16x16x32_bf16 v[90:93], v[150:153], v[246:249], v[90:93]
	v_mfma_f32_16x16x32_bf16 v[82:85], v[184:187], v[246:249], v[82:85]
	v_mfma_f32_16x16x32_bf16 v[132:135], v[158:161], v[226:229], v[132:135]
	v_mfma_f32_16x16x32_bf16 v[128:131], v[188:191], v[226:229], v[128:131]
	v_mfma_f32_16x16x32_bf16 v[124:127], v[158:161], v[234:237], v[124:127]
	v_mfma_f32_16x16x32_bf16 v[120:123], v[188:191], v[234:237], v[120:123]
	v_mfma_f32_16x16x32_bf16 v[106:109], v[158:161], v[242:245], v[106:109]
	v_mfma_f32_16x16x32_bf16 v[98:101], v[188:191], v[242:245], v[98:101]
	v_mfma_f32_16x16x32_bf16 v[90:93], v[158:161], v[170:173], v[90:93]
	v_mfma_f32_16x16x32_bf16 v[82:85], v[188:191], v[170:173], v[82:85]
	v_mfma_f32_16x16x32_bf16 v[116:119], v[192:195], v[222:225], v[116:119]
	v_mfma_f32_16x16x32_bf16 v[102:105], v[214:217], v[222:225], v[102:105]
	v_mfma_f32_16x16x32_bf16 v[94:97], v[192:195], v[230:233], v[94:97]
	v_mfma_f32_16x16x32_bf16 v[86:89], v[214:217], v[230:233], v[86:89]
	v_mfma_f32_16x16x32_bf16 v[78:81], v[192:195], v[238:241], v[78:81]
	v_mfma_f32_16x16x32_bf16 v[74:77], v[214:217], v[238:241], v[74:77]
	v_mfma_f32_16x16x32_bf16 v[70:73], v[192:195], v[246:249], v[70:73]
	v_mfma_f32_16x16x32_bf16 v[66:69], v[214:217], v[246:249], v[66:69]
	v_mfma_f32_16x16x32_bf16 v[116:119], v[196:199], v[226:229], v[116:119]
	v_mfma_f32_16x16x32_bf16 v[102:105], v[218:221], v[226:229], v[102:105]
	v_mfma_f32_16x16x32_bf16 v[94:97], v[196:199], v[234:237], v[94:97]
	v_mfma_f32_16x16x32_bf16 v[86:89], v[218:221], v[234:237], v[86:89]
	v_mfma_f32_16x16x32_bf16 v[78:81], v[196:199], v[242:245], v[78:81]
	v_mfma_f32_16x16x32_bf16 v[74:77], v[218:221], v[242:245], v[74:77]
	v_mfma_f32_16x16x32_bf16 v[70:73], v[196:199], v[170:173], v[70:73]
	v_mfma_f32_16x16x32_bf16 v[66:69], v[218:221], v[170:173], v[66:69]
	s_barrier
	s_add_i32 s74, s74, s54
	v_lshl_add_u64 v[154:155], s[8:9], 0, v[136:137]
	s_mov_b32 m0, s74
	ds_read_b128 v[170:173], v156 offset:16384
	ds_read_b128 v[222:225], v156 offset:17408
	ds_read_b128 v[226:229], v156 offset:18432
	ds_read_b128 v[230:233], v156 offset:19456
	ds_read_b128 v[234:237], v156 offset:20480
	ds_read_b128 v[238:241], v156 offset:21504
	ds_read_b128 v[242:245], v156 offset:22528
	ds_read_b128 v[246:249], v156 offset:23552
	global_load_lds_dwordx4 v[154:155], off
	s_add_i32 m0, s74, 0x2000
	s_add_u32 s74, s8, 0x80000
	v_lshl_add_u64 v[162:163], s[8:9], 0, v[140:141]
	s_addc_u32 s75, s9, 0
	s_add_i32 s73, s73, s54
	global_load_lds_dwordx4 v[162:163], off
	v_lshl_add_u64 v[200:201], s[74:75], 0, v[136:137]
	s_mov_b32 m0, s73
	v_lshl_add_u64 v[250:251], s[94:95], 0, v[138:139]
	global_load_lds_dwordx4 v[200:201], off
	v_lshl_add_u64 v[200:201], s[74:75], 0, v[140:141]
	s_add_i32 m0, s73, 0x2000
	s_nop 0
	global_load_lds_dwordx4 v[200:201], off
	v_lshl_add_u64 v[200:201], s[94:95], 0, v[110:111]
	s_mov_b32 m0, s17
	s_nop 0
	global_load_lds_dwordx4 v[200:201], off
	s_mov_b32 m0, s58
	s_nop 0
	global_load_lds_dwordx4 v[250:251], off
	s_waitcnt vmcnt(8) lgkmcnt(0)
	s_barrier
	v_mfma_f32_16x16x32_bf16 v[62:65], v[150:153], v[170:173], v[62:65]
	v_mfma_f32_16x16x32_bf16 v[58:61], v[184:187], v[170:173], v[58:61]
	v_mfma_f32_16x16x32_bf16 v[54:57], v[150:153], v[226:229], v[54:57]
	v_mfma_f32_16x16x32_bf16 v[50:53], v[184:187], v[226:229], v[50:53]
	v_mfma_f32_16x16x32_bf16 v[42:45], v[150:153], v[234:237], v[42:45]
	v_mfma_f32_16x16x32_bf16 v[34:37], v[184:187], v[234:237], v[34:37]
	v_mfma_f32_16x16x32_bf16 v[26:29], v[150:153], v[242:245], v[26:29]
	v_mfma_f32_16x16x32_bf16 v[18:21], v[184:187], v[242:245], v[18:21]
	v_mfma_f32_16x16x32_bf16 v[62:65], v[158:161], v[222:225], v[62:65]
	v_mfma_f32_16x16x32_bf16 v[58:61], v[188:191], v[222:225], v[58:61]
	v_mfma_f32_16x16x32_bf16 v[54:57], v[158:161], v[230:233], v[54:57]
	v_mfma_f32_16x16x32_bf16 v[50:53], v[188:191], v[230:233], v[50:53]
	v_mfma_f32_16x16x32_bf16 v[42:45], v[158:161], v[238:241], v[42:45]
	v_mfma_f32_16x16x32_bf16 v[34:37], v[188:191], v[238:241], v[34:37]
	v_mfma_f32_16x16x32_bf16 v[26:29], v[158:161], v[246:249], v[26:29]
	v_mfma_f32_16x16x32_bf16 v[18:21], v[188:191], v[246:249], v[18:21]
	v_mfma_f32_16x16x32_bf16 v[46:49], v[192:195], v[170:173], v[46:49]
	v_mfma_f32_16x16x32_bf16 v[38:41], v[214:217], v[170:173], v[38:41]
	v_mfma_f32_16x16x32_bf16 v[30:33], v[192:195], v[226:229], v[30:33]
	v_mfma_f32_16x16x32_bf16 v[22:25], v[214:217], v[226:229], v[22:25]
	v_mfma_f32_16x16x32_bf16 v[14:17], v[192:195], v[234:237], v[14:17]
	v_mfma_f32_16x16x32_bf16 v[10:13], v[214:217], v[234:237], v[10:13]
	v_mfma_f32_16x16x32_bf16 v[6:9], v[192:195], v[242:245], v[6:9]
	v_mfma_f32_16x16x32_bf16 v[2:5], v[214:217], v[242:245], v[2:5]
	v_mfma_f32_16x16x32_bf16 v[46:49], v[196:199], v[222:225], v[46:49]
	v_mfma_f32_16x16x32_bf16 v[38:41], v[218:221], v[222:225], v[38:41]
	v_mfma_f32_16x16x32_bf16 v[30:33], v[196:199], v[230:233], v[30:33]
	v_mfma_f32_16x16x32_bf16 v[22:25], v[218:221], v[230:233], v[22:25]
	v_mfma_f32_16x16x32_bf16 v[14:17], v[196:199], v[238:241], v[14:17]
	v_mfma_f32_16x16x32_bf16 v[10:13], v[218:221], v[238:241], v[10:13]
	v_mfma_f32_16x16x32_bf16 v[6:9], v[196:199], v[246:249], v[6:9]
	v_mfma_f32_16x16x32_bf16 v[2:5], v[218:221], v[246:249], v[2:5]
	s_barrier
	s_add_i32 s73, 0, 0x18000
	v_add_u32_e32 v157, s73, v1
	s_add_i32 s88, 0, 0x1c000
	ds_read_b128 v[150:153], v157
	ds_read_b128 v[158:161], v157 offset:1024
	ds_read_b128 v[170:173], v157 offset:2048
	ds_read_b128 v[184:187], v157 offset:3072
	v_add_u32_e32 v157, s88, v1
	ds_read_b128 v[188:191], v157
	ds_read_b128 v[192:195], v157 offset:1024
	ds_read_b128 v[196:199], v157 offset:2048
	ds_read_b128 v[214:217], v157 offset:3072
	s_add_u32 s74, s94, 0x80000
	s_addc_u32 s75, s95, 0
	s_mov_b32 m0, s59
	v_lshl_add_u64 v[206:207], s[74:75], 0, v[110:111]
	ds_read_b128 v[218:221], v156 offset:32768
	ds_read_b128 v[222:225], v156 offset:33792
	ds_read_b128 v[226:229], v156 offset:34816
	ds_read_b128 v[230:233], v156 offset:35840
	ds_read_b128 v[234:237], v156 offset:36864
	ds_read_b128 v[238:241], v156 offset:37888
	ds_read_b128 v[242:245], v156 offset:38912
	ds_read_b128 v[246:249], v156 offset:39936
	global_load_lds_dwordx4 v[206:207], off
	v_lshl_add_u64 v[206:207], s[74:75], 0, v[138:139]
	s_mov_b32 m0, s60
	s_nop 0
	global_load_lds_dwordx4 v[206:207], off
	s_waitcnt vmcnt(8) lgkmcnt(0)
	s_barrier
	v_mfma_f32_16x16x32_bf16 v[132:135], v[150:153], v[218:221], v[132:135]
	v_mfma_f32_16x16x32_bf16 v[128:131], v[170:173], v[218:221], v[128:131]
	v_mfma_f32_16x16x32_bf16 v[124:127], v[150:153], v[226:229], v[124:127]
	v_mfma_f32_16x16x32_bf16 v[120:123], v[170:173], v[226:229], v[120:123]
	v_mfma_f32_16x16x32_bf16 v[106:109], v[150:153], v[234:237], v[106:109]
	v_mfma_f32_16x16x32_bf16 v[98:101], v[170:173], v[234:237], v[98:101]
	v_mfma_f32_16x16x32_bf16 v[90:93], v[150:153], v[242:245], v[90:93]
	v_mfma_f32_16x16x32_bf16 v[82:85], v[170:173], v[242:245], v[82:85]
	v_mfma_f32_16x16x32_bf16 v[132:135], v[158:161], v[222:225], v[132:135]
	v_mfma_f32_16x16x32_bf16 v[128:131], v[184:187], v[222:225], v[128:131]
	v_mfma_f32_16x16x32_bf16 v[124:127], v[158:161], v[230:233], v[124:127]
	v_mfma_f32_16x16x32_bf16 v[120:123], v[184:187], v[230:233], v[120:123]
	v_mfma_f32_16x16x32_bf16 v[106:109], v[158:161], v[238:241], v[106:109]
	v_mfma_f32_16x16x32_bf16 v[98:101], v[184:187], v[238:241], v[98:101]
	v_mfma_f32_16x16x32_bf16 v[90:93], v[158:161], v[246:249], v[90:93]
	v_mfma_f32_16x16x32_bf16 v[82:85], v[184:187], v[246:249], v[82:85]
	v_mfma_f32_16x16x32_bf16 v[116:119], v[188:191], v[218:221], v[116:119]
	v_mfma_f32_16x16x32_bf16 v[102:105], v[196:199], v[218:221], v[102:105]
	v_mfma_f32_16x16x32_bf16 v[94:97], v[188:191], v[226:229], v[94:97]
	v_mfma_f32_16x16x32_bf16 v[86:89], v[196:199], v[226:229], v[86:89]
	v_mfma_f32_16x16x32_bf16 v[78:81], v[188:191], v[234:237], v[78:81]
	v_mfma_f32_16x16x32_bf16 v[74:77], v[196:199], v[234:237], v[74:77]
	v_mfma_f32_16x16x32_bf16 v[70:73], v[188:191], v[242:245], v[70:73]
	v_mfma_f32_16x16x32_bf16 v[66:69], v[196:199], v[242:245], v[66:69]
	v_mfma_f32_16x16x32_bf16 v[116:119], v[192:195], v[222:225], v[116:119]
	v_mfma_f32_16x16x32_bf16 v[102:105], v[214:217], v[222:225], v[102:105]
	v_mfma_f32_16x16x32_bf16 v[94:97], v[192:195], v[230:233], v[94:97]
	v_mfma_f32_16x16x32_bf16 v[86:89], v[214:217], v[230:233], v[86:89]
	v_mfma_f32_16x16x32_bf16 v[78:81], v[192:195], v[238:241], v[78:81]
	v_mfma_f32_16x16x32_bf16 v[74:77], v[214:217], v[238:241], v[74:77]
	v_mfma_f32_16x16x32_bf16 v[70:73], v[192:195], v[246:249], v[70:73]
	v_mfma_f32_16x16x32_bf16 v[66:69], v[214:217], v[246:249], v[66:69]
	s_barrier
	s_add_i32 s73, s73, s54
	v_lshl_add_u64 v[154:155], v[154:155], 0, s[26:27]
	s_mov_b32 m0, s73
	ds_read_b128 v[218:221], v156 offset:49152
	ds_read_b128 v[222:225], v156 offset:50176
	ds_read_b128 v[226:229], v156 offset:51200
	ds_read_b128 v[230:233], v156 offset:52224
	ds_read_b128 v[234:237], v156 offset:53248
	ds_read_b128 v[238:241], v156 offset:54272
	ds_read_b128 v[242:245], v156 offset:55296
	ds_read_b128 v[246:249], v156 offset:56320
	global_load_lds_dwordx4 v[154:155], off
	s_add_i32 m0, s73, 0x2000
	s_add_u32 s8, s8, 0x80080
	v_lshl_add_u64 v[154:155], v[162:163], 0, s[26:27]
	s_addc_u32 s9, s9, 0
	s_add_i32 s73, s88, s54
	global_load_lds_dwordx4 v[154:155], off
	v_lshl_add_u64 v[154:155], s[8:9], 0, v[136:137]
	s_mov_b32 m0, s73
	s_nop 0
	global_load_lds_dwordx4 v[154:155], off
	v_lshl_add_u64 v[154:155], s[8:9], 0, v[140:141]
	s_add_i32 m0, s73, 0x2000
	s_nop 0
	global_load_lds_dwordx4 v[154:155], off
	v_lshl_add_u64 v[154:155], v[200:201], 0, s[26:27]
	s_mov_b32 m0, s62
	s_nop 0
	global_load_lds_dwordx4 v[154:155], off
	v_lshl_add_u64 v[154:155], v[250:251], 0, s[26:27]
	s_mov_b32 m0, s63
	s_nop 0
	global_load_lds_dwordx4 v[154:155], off
	s_waitcnt vmcnt(8) lgkmcnt(0)
	s_barrier
	v_mfma_f32_16x16x32_bf16 v[62:65], v[150:153], v[218:221], v[62:65]
	v_mfma_f32_16x16x32_bf16 v[58:61], v[170:173], v[218:221], v[58:61]
	v_mfma_f32_16x16x32_bf16 v[54:57], v[150:153], v[226:229], v[54:57]
	v_mfma_f32_16x16x32_bf16 v[50:53], v[170:173], v[226:229], v[50:53]
	v_mfma_f32_16x16x32_bf16 v[42:45], v[150:153], v[234:237], v[42:45]
	v_mfma_f32_16x16x32_bf16 v[34:37], v[170:173], v[234:237], v[34:37]
	v_mfma_f32_16x16x32_bf16 v[26:29], v[150:153], v[242:245], v[26:29]
	v_mfma_f32_16x16x32_bf16 v[18:21], v[170:173], v[242:245], v[18:21]
	v_mfma_f32_16x16x32_bf16 v[62:65], v[158:161], v[222:225], v[62:65]
	v_mfma_f32_16x16x32_bf16 v[58:61], v[184:187], v[222:225], v[58:61]
	v_mfma_f32_16x16x32_bf16 v[54:57], v[158:161], v[230:233], v[54:57]
	v_mfma_f32_16x16x32_bf16 v[50:53], v[184:187], v[230:233], v[50:53]
	v_mfma_f32_16x16x32_bf16 v[42:45], v[158:161], v[238:241], v[42:45]
	v_mfma_f32_16x16x32_bf16 v[34:37], v[184:187], v[238:241], v[34:37]
	v_mfma_f32_16x16x32_bf16 v[26:29], v[158:161], v[246:249], v[26:29]
	v_mfma_f32_16x16x32_bf16 v[18:21], v[184:187], v[246:249], v[18:21]
	v_mfma_f32_16x16x32_bf16 v[46:49], v[188:191], v[218:221], v[46:49]
	v_mfma_f32_16x16x32_bf16 v[38:41], v[196:199], v[218:221], v[38:41]
	v_mfma_f32_16x16x32_bf16 v[30:33], v[188:191], v[226:229], v[30:33]
	v_mfma_f32_16x16x32_bf16 v[22:25], v[196:199], v[226:229], v[22:25]
	v_mfma_f32_16x16x32_bf16 v[14:17], v[188:191], v[234:237], v[14:17]
	v_mfma_f32_16x16x32_bf16 v[10:13], v[196:199], v[234:237], v[10:13]
	v_mfma_f32_16x16x32_bf16 v[6:9], v[188:191], v[242:245], v[6:9]
	v_mfma_f32_16x16x32_bf16 v[2:5], v[196:199], v[242:245], v[2:5]
	v_mfma_f32_16x16x32_bf16 v[46:49], v[192:195], v[222:225], v[46:49]
	v_mfma_f32_16x16x32_bf16 v[38:41], v[214:217], v[222:225], v[38:41]
	v_mfma_f32_16x16x32_bf16 v[30:33], v[192:195], v[230:233], v[30:33]
	v_mfma_f32_16x16x32_bf16 v[22:25], v[214:217], v[230:233], v[22:25]
	v_mfma_f32_16x16x32_bf16 v[14:17], v[192:195], v[238:241], v[14:17]
	v_mfma_f32_16x16x32_bf16 v[10:13], v[214:217], v[238:241], v[10:13]
	v_mfma_f32_16x16x32_bf16 v[6:9], v[192:195], v[246:249], v[6:9]
	v_mfma_f32_16x16x32_bf16 v[2:5], v[214:217], v[246:249], v[2:5]
	s_barrier
	s_add_u32 s92, s92, 0x100
	s_addc_u32 s93, s93, 0
	s_add_u32 s70, s70, 0x100
	s_addc_u32 s71, s71, 0
	s_cmp_ge_u32 s72, s67
	s_mov_b32 s8, s72
	s_cbranch_scc0 .LBB0_553
	s_and_b64 vcc, exec, s[44:45]
	s_cbranch_vccnz .LBB0_558
	s_cmp_lt_i32 s57, 0
	s_mov_b64 s[8:9], -1
	s_movk_i32 s94, 0x1fff
	s_cbranch_scc1 .LBB0_559

.LBB0_708:
	s_add_u32 s8, s86, 0xfff80080
	s_addc_u32 s9, s87, -1
	s_add_i32 s67, 0, 0x10000
	s_cmp_eq_u32 s66, 28
	s_cselect_b32 s93, s41, s9
	s_cselect_b32 s92, s45, s8
	v_add_u32_e32 v150, s67, v152
	s_cselect_b32 s9, s43, s65
	s_cselect_b32 s8, s63, s64
	s_add_i32 s70, 0, 0x14000
	ds_read_b128 v[146:149], v150
	ds_read_b128 v[156:159], v150 offset:1024
	ds_read_b128 v[160:163], v150 offset:2048
	ds_read_b128 v[170:173], v150 offset:3072
	v_add_u32_e32 v150, s70, v152
	ds_read_b128 v[184:187], v150
	ds_read_b128 v[188:191], v150 offset:1024
	ds_read_b128 v[192:195], v150 offset:2048
	ds_read_b128 v[196:199], v150 offset:3072
	v_lshl_add_u64 v[150:151], s[86:87], 0, v[142:143]
	s_add_i32 m0, s57, 0xc000
	ds_read_b128 v[214:217], v154
	ds_read_b128 v[218:221], v154 offset:1024
	ds_read_b128 v[222:225], v154 offset:2048
	ds_read_b128 v[226:229], v154 offset:3072
	ds_read_b128 v[230:233], v154 offset:4096
	ds_read_b128 v[234:237], v154 offset:5120
	ds_read_b128 v[238:241], v154 offset:6144
	ds_read_b128 v[242:245], v154 offset:7168
	global_load_lds_dwordx4 v[150:151], off
	v_lshl_add_u64 v[150:151], s[86:87], 0, v[144:145]
	s_add_i32 m0, s57, 0xe000
	s_nop 0
	global_load_lds_dwordx4 v[150:151], off
	s_waitcnt vmcnt(8) lgkmcnt(0)
	s_barrier
	v_mfma_f32_16x16x32_bf16 v[132:135], v[146:149], v[214:217], v[132:135]
	v_mfma_f32_16x16x32_bf16 v[128:131], v[160:163], v[214:217], v[128:131]
	v_mfma_f32_16x16x32_bf16 v[116:119], v[146:149], v[222:225], v[116:119]
	v_mfma_f32_16x16x32_bf16 v[106:109], v[160:163], v[222:225], v[106:109]
	v_mfma_f32_16x16x32_bf16 v[94:97], v[146:149], v[230:233], v[94:97]
	v_mfma_f32_16x16x32_bf16 v[90:93], v[160:163], v[230:233], v[90:93]
	v_mfma_f32_16x16x32_bf16 v[78:81], v[146:149], v[238:241], v[78:81]
	v_mfma_f32_16x16x32_bf16 v[74:77], v[160:163], v[238:241], v[74:77]
	v_mfma_f32_16x16x32_bf16 v[132:135], v[156:159], v[218:221], v[132:135]
	v_mfma_f32_16x16x32_bf16 v[128:131], v[170:173], v[218:221], v[128:131]
	v_mfma_f32_16x16x32_bf16 v[116:119], v[156:159], v[226:229], v[116:119]
	v_mfma_f32_16x16x32_bf16 v[106:109], v[170:173], v[226:229], v[106:109]
	v_mfma_f32_16x16x32_bf16 v[94:97], v[156:159], v[234:237], v[94:97]
	v_mfma_f32_16x16x32_bf16 v[90:93], v[170:173], v[234:237], v[90:93]
	v_mfma_f32_16x16x32_bf16 v[78:81], v[156:159], v[242:245], v[78:81]
	v_mfma_f32_16x16x32_bf16 v[74:77], v[170:173], v[242:245], v[74:77]
	v_mfma_f32_16x16x32_bf16 v[124:127], v[184:187], v[214:217], v[124:127]
	v_mfma_f32_16x16x32_bf16 v[120:123], v[192:195], v[214:217], v[120:123]
	v_mfma_f32_16x16x32_bf16 v[102:105], v[184:187], v[222:225], v[102:105]
	v_mfma_f32_16x16x32_bf16 v[98:101], v[192:195], v[222:225], v[98:101]
	v_mfma_f32_16x16x32_bf16 v[86:89], v[184:187], v[230:233], v[86:89]
	v_mfma_f32_16x16x32_bf16 v[82:85], v[192:195], v[230:233], v[82:85]
	v_mfma_f32_16x16x32_bf16 v[70:73], v[184:187], v[238:241], v[70:73]
	v_mfma_f32_16x16x32_bf16 v[66:69], v[192:195], v[238:241], v[66:69]
	v_mfma_f32_16x16x32_bf16 v[124:127], v[188:191], v[218:221], v[124:127]
	v_mfma_f32_16x16x32_bf16 v[120:123], v[196:199], v[218:221], v[120:123]
	v_mfma_f32_16x16x32_bf16 v[102:105], v[188:191], v[226:229], v[102:105]
	v_mfma_f32_16x16x32_bf16 v[98:101], v[196:199], v[226:229], v[98:101]
	v_mfma_f32_16x16x32_bf16 v[86:89], v[188:191], v[234:237], v[86:89]
	v_mfma_f32_16x16x32_bf16 v[82:85], v[196:199], v[234:237], v[82:85]
	v_mfma_f32_16x16x32_bf16 v[70:73], v[188:191], v[242:245], v[70:73]
	v_mfma_f32_16x16x32_bf16 v[66:69], v[196:199], v[242:245], v[66:69]
	s_barrier
	s_add_i32 s67, s67, s54
	v_lshl_add_u64 v[150:151], s[8:9], 0, v[136:137]
	s_mov_b32 m0, s67
	ds_read_b128 v[214:217], v154 offset:16384
	ds_read_b128 v[218:221], v154 offset:17408
	ds_read_b128 v[222:225], v154 offset:18432
	ds_read_b128 v[226:229], v154 offset:19456
	ds_read_b128 v[230:233], v154 offset:20480
	ds_read_b128 v[234:237], v154 offset:21504
	ds_read_b128 v[238:241], v154 offset:22528
	ds_read_b128 v[242:245], v154 offset:23552
	global_load_lds_dwordx4 v[150:151], off
	s_add_i32 m0, s67, 0x2000
	s_add_u32 s68, s8, 0x80000
	v_lshl_add_u64 v[200:201], s[8:9], 0, v[140:141]
	s_addc_u32 s69, s9, 0
	s_add_i32 s67, s70, s54
	global_load_lds_dwordx4 v[200:201], off
	v_lshl_add_u64 v[206:207], s[68:69], 0, v[136:137]
	s_mov_b32 m0, s67
	v_lshl_add_u64 v[246:247], s[92:93], 0, v[138:139]
	global_load_lds_dwordx4 v[206:207], off
	v_lshl_add_u64 v[206:207], s[68:69], 0, v[140:141]
	s_add_i32 m0, s67, 0x2000
	s_nop 0
	global_load_lds_dwordx4 v[206:207], off
	v_lshl_add_u64 v[206:207], s[92:93], 0, v[110:111]
	s_mov_b32 m0, s57
	s_nop 0
	global_load_lds_dwordx4 v[206:207], off
	s_mov_b32 m0, s58
	s_nop 0
	global_load_lds_dwordx4 v[246:247], off
	s_waitcnt vmcnt(8) lgkmcnt(0)
	s_barrier
	v_mfma_f32_16x16x32_bf16 v[62:65], v[146:149], v[214:217], v[62:65]
	v_mfma_f32_16x16x32_bf16 v[58:61], v[160:163], v[214:217], v[58:61]
	v_mfma_f32_16x16x32_bf16 v[46:49], v[146:149], v[222:225], v[46:49]
	v_mfma_f32_16x16x32_bf16 v[42:45], v[160:163], v[222:225], v[42:45]
	v_mfma_f32_16x16x32_bf16 v[30:33], v[146:149], v[230:233], v[30:33]
	v_mfma_f32_16x16x32_bf16 v[26:29], v[160:163], v[230:233], v[26:29]
	v_mfma_f32_16x16x32_bf16 v[14:17], v[146:149], v[238:241], v[14:17]
	v_mfma_f32_16x16x32_bf16 v[10:13], v[160:163], v[238:241], v[10:13]
	v_mfma_f32_16x16x32_bf16 v[62:65], v[156:159], v[218:221], v[62:65]
	v_mfma_f32_16x16x32_bf16 v[58:61], v[170:173], v[218:221], v[58:61]
	v_mfma_f32_16x16x32_bf16 v[46:49], v[156:159], v[226:229], v[46:49]
	v_mfma_f32_16x16x32_bf16 v[42:45], v[170:173], v[226:229], v[42:45]
	v_mfma_f32_16x16x32_bf16 v[30:33], v[156:159], v[234:237], v[30:33]
	v_mfma_f32_16x16x32_bf16 v[26:29], v[170:173], v[234:237], v[26:29]
	v_mfma_f32_16x16x32_bf16 v[14:17], v[156:159], v[242:245], v[14:17]
	v_mfma_f32_16x16x32_bf16 v[10:13], v[170:173], v[242:245], v[10:13]
	v_mfma_f32_16x16x32_bf16 v[54:57], v[184:187], v[214:217], v[54:57]
	v_mfma_f32_16x16x32_bf16 v[50:53], v[192:195], v[214:217], v[50:53]
	v_mfma_f32_16x16x32_bf16 v[38:41], v[184:187], v[222:225], v[38:41]
	v_mfma_f32_16x16x32_bf16 v[34:37], v[192:195], v[222:225], v[34:37]
	v_mfma_f32_16x16x32_bf16 v[22:25], v[184:187], v[230:233], v[22:25]
	v_mfma_f32_16x16x32_bf16 v[18:21], v[192:195], v[230:233], v[18:21]
	v_mfma_f32_16x16x32_bf16 v[6:9], v[184:187], v[238:241], v[6:9]
	v_mfma_f32_16x16x32_bf16 v[2:5], v[192:195], v[238:241], v[2:5]
	v_mfma_f32_16x16x32_bf16 v[54:57], v[188:191], v[218:221], v[54:57]
	v_mfma_f32_16x16x32_bf16 v[50:53], v[196:199], v[218:221], v[50:53]
	v_mfma_f32_16x16x32_bf16 v[38:41], v[188:191], v[226:229], v[38:41]
	v_mfma_f32_16x16x32_bf16 v[34:37], v[196:199], v[226:229], v[34:37]
	v_mfma_f32_16x16x32_bf16 v[22:25], v[188:191], v[234:237], v[22:25]
	v_mfma_f32_16x16x32_bf16 v[18:21], v[196:199], v[234:237], v[18:21]
	v_mfma_f32_16x16x32_bf16 v[6:9], v[188:191], v[242:245], v[6:9]
	v_mfma_f32_16x16x32_bf16 v[2:5], v[196:199], v[242:245], v[2:5]
	s_barrier
	s_add_i32 s67, 0, 0x18000
	v_add_u32_e32 v155, s67, v152
	s_add_i32 s70, 0, 0x1c000
	ds_read_b128 v[146:149], v155
	ds_read_b128 v[156:159], v155 offset:1024
	ds_read_b128 v[160:163], v155 offset:2048
	ds_read_b128 v[170:173], v155 offset:3072
	v_add_u32_e32 v155, s70, v152
	ds_read_b128 v[184:187], v155
	ds_read_b128 v[188:191], v155 offset:1024
	ds_read_b128 v[192:195], v155 offset:2048
	ds_read_b128 v[196:199], v155 offset:3072
	s_add_u32 s68, s92, 0x80000
	s_addc_u32 s69, s93, 0
	s_mov_b32 m0, s59
	v_lshl_add_u64 v[248:249], s[68:69], 0, v[110:111]
	ds_read_b128 v[214:217], v154 offset:32768
	ds_read_b128 v[218:221], v154 offset:33792
	ds_read_b128 v[222:225], v154 offset:34816
	ds_read_b128 v[226:229], v154 offset:35840
	ds_read_b128 v[230:233], v154 offset:36864
	ds_read_b128 v[234:237], v154 offset:37888
	ds_read_b128 v[238:241], v154 offset:38912
	ds_read_b128 v[242:245], v154 offset:39936
	global_load_lds_dwordx4 v[248:249], off
	v_lshl_add_u64 v[248:249], s[68:69], 0, v[138:139]
	s_mov_b32 m0, s60
	s_nop 0
	global_load_lds_dwordx4 v[248:249], off
	s_waitcnt vmcnt(8) lgkmcnt(0)
	s_barrier
	v_mfma_f32_16x16x32_bf16 v[132:135], v[146:149], v[214:217], v[132:135]
	v_mfma_f32_16x16x32_bf16 v[128:131], v[160:163], v[214:217], v[128:131]
	v_mfma_f32_16x16x32_bf16 v[116:119], v[146:149], v[222:225], v[116:119]
	v_mfma_f32_16x16x32_bf16 v[106:109], v[160:163], v[222:225], v[106:109]
	v_mfma_f32_16x16x32_bf16 v[94:97], v[146:149], v[230:233], v[94:97]
	v_mfma_f32_16x16x32_bf16 v[90:93], v[160:163], v[230:233], v[90:93]
	v_mfma_f32_16x16x32_bf16 v[78:81], v[146:149], v[238:241], v[78:81]
	v_mfma_f32_16x16x32_bf16 v[74:77], v[160:163], v[238:241], v[74:77]
	v_mfma_f32_16x16x32_bf16 v[132:135], v[156:159], v[218:221], v[132:135]
	v_mfma_f32_16x16x32_bf16 v[128:131], v[170:173], v[218:221], v[128:131]
	v_mfma_f32_16x16x32_bf16 v[116:119], v[156:159], v[226:229], v[116:119]
	v_mfma_f32_16x16x32_bf16 v[106:109], v[170:173], v[226:229], v[106:109]
	v_mfma_f32_16x16x32_bf16 v[94:97], v[156:159], v[234:237], v[94:97]
	v_mfma_f32_16x16x32_bf16 v[90:93], v[170:173], v[234:237], v[90:93]
	v_mfma_f32_16x16x32_bf16 v[78:81], v[156:159], v[242:245], v[78:81]
	v_mfma_f32_16x16x32_bf16 v[74:77], v[170:173], v[242:245], v[74:77]
	v_mfma_f32_16x16x32_bf16 v[124:127], v[184:187], v[214:217], v[124:127]
	v_mfma_f32_16x16x32_bf16 v[120:123], v[192:195], v[214:217], v[120:123]
	v_mfma_f32_16x16x32_bf16 v[102:105], v[184:187], v[222:225], v[102:105]
	v_mfma_f32_16x16x32_bf16 v[98:101], v[192:195], v[222:225], v[98:101]
	v_mfma_f32_16x16x32_bf16 v[86:89], v[184:187], v[230:233], v[86:89]
	v_mfma_f32_16x16x32_bf16 v[82:85], v[192:195], v[230:233], v[82:85]
	v_mfma_f32_16x16x32_bf16 v[70:73], v[184:187], v[238:241], v[70:73]
	v_mfma_f32_16x16x32_bf16 v[66:69], v[192:195], v[238:241], v[66:69]
	v_mfma_f32_16x16x32_bf16 v[124:127], v[188:191], v[218:221], v[124:127]
	v_mfma_f32_16x16x32_bf16 v[120:123], v[196:199], v[218:221], v[120:123]
	v_mfma_f32_16x16x32_bf16 v[102:105], v[188:191], v[226:229], v[102:105]
	v_mfma_f32_16x16x32_bf16 v[98:101], v[196:199], v[226:229], v[98:101]
	v_mfma_f32_16x16x32_bf16 v[86:89], v[188:191], v[234:237], v[86:89]
	v_mfma_f32_16x16x32_bf16 v[82:85], v[196:199], v[234:237], v[82:85]
	v_mfma_f32_16x16x32_bf16 v[70:73], v[188:191], v[242:245], v[70:73]
	v_mfma_f32_16x16x32_bf16 v[66:69], v[196:199], v[242:245], v[66:69]
	s_barrier
	s_add_i32 s67, s67, s54
	v_lshl_add_u64 v[150:151], v[150:151], 0, s[26:27]
	s_mov_b32 m0, s67
	ds_read_b128 v[214:217], v154 offset:49152
	ds_read_b128 v[218:221], v154 offset:50176
	ds_read_b128 v[222:225], v154 offset:51200
	ds_read_b128 v[226:229], v154 offset:52224
	ds_read_b128 v[230:233], v154 offset:53248
	ds_read_b128 v[234:237], v154 offset:54272
	ds_read_b128 v[238:241], v154 offset:55296
	ds_read_b128 v[242:245], v154 offset:56320
	global_load_lds_dwordx4 v[150:151], off
	s_add_i32 m0, s67, 0x2000
	s_add_u32 s8, s8, 0x80080
	v_lshl_add_u64 v[150:151], v[200:201], 0, s[26:27]
	s_addc_u32 s9, s9, 0
	s_add_i32 s67, s70, s54
	global_load_lds_dwordx4 v[150:151], off
	v_lshl_add_u64 v[150:151], s[8:9], 0, v[136:137]
	s_mov_b32 m0, s67
	s_nop 0
	global_load_lds_dwordx4 v[150:151], off
	v_lshl_add_u64 v[150:151], s[8:9], 0, v[140:141]
	s_add_i32 m0, s67, 0x2000
	s_nop 0
	global_load_lds_dwordx4 v[150:151], off
	v_lshl_add_u64 v[150:151], v[206:207], 0, s[26:27]
	s_mov_b32 m0, s37
	s_nop 0
	global_load_lds_dwordx4 v[150:151], off
	v_lshl_add_u64 v[150:151], v[246:247], 0, s[26:27]
	s_mov_b32 m0, s61
	s_nop 0
	global_load_lds_dwordx4 v[150:151], off
	s_waitcnt vmcnt(8) lgkmcnt(0)
	s_barrier
	v_mfma_f32_16x16x32_bf16 v[62:65], v[146:149], v[214:217], v[62:65]
	v_mfma_f32_16x16x32_bf16 v[58:61], v[160:163], v[214:217], v[58:61]
	v_mfma_f32_16x16x32_bf16 v[46:49], v[146:149], v[222:225], v[46:49]
	v_mfma_f32_16x16x32_bf16 v[42:45], v[160:163], v[222:225], v[42:45]
	v_mfma_f32_16x16x32_bf16 v[30:33], v[146:149], v[230:233], v[30:33]
	v_mfma_f32_16x16x32_bf16 v[26:29], v[160:163], v[230:233], v[26:29]
	v_mfma_f32_16x16x32_bf16 v[14:17], v[146:149], v[238:241], v[14:17]
	v_mfma_f32_16x16x32_bf16 v[10:13], v[160:163], v[238:241], v[10:13]
	v_mfma_f32_16x16x32_bf16 v[62:65], v[156:159], v[218:221], v[62:65]
	v_mfma_f32_16x16x32_bf16 v[58:61], v[170:173], v[218:221], v[58:61]
	v_mfma_f32_16x16x32_bf16 v[46:49], v[156:159], v[226:229], v[46:49]
	v_mfma_f32_16x16x32_bf16 v[42:45], v[170:173], v[226:229], v[42:45]
	v_mfma_f32_16x16x32_bf16 v[30:33], v[156:159], v[234:237], v[30:33]
	v_mfma_f32_16x16x32_bf16 v[26:29], v[170:173], v[234:237], v[26:29]
	v_mfma_f32_16x16x32_bf16 v[14:17], v[156:159], v[242:245], v[14:17]
	v_mfma_f32_16x16x32_bf16 v[10:13], v[170:173], v[242:245], v[10:13]
	v_mfma_f32_16x16x32_bf16 v[54:57], v[184:187], v[214:217], v[54:57]
	v_mfma_f32_16x16x32_bf16 v[50:53], v[192:195], v[214:217], v[50:53]
	v_mfma_f32_16x16x32_bf16 v[38:41], v[184:187], v[222:225], v[38:41]
	v_mfma_f32_16x16x32_bf16 v[34:37], v[192:195], v[222:225], v[34:37]
	v_mfma_f32_16x16x32_bf16 v[22:25], v[184:187], v[230:233], v[22:25]
	v_mfma_f32_16x16x32_bf16 v[18:21], v[192:195], v[230:233], v[18:21]
	v_mfma_f32_16x16x32_bf16 v[6:9], v[184:187], v[238:241], v[6:9]
	v_mfma_f32_16x16x32_bf16 v[2:5], v[192:195], v[238:241], v[2:5]
	v_mfma_f32_16x16x32_bf16 v[54:57], v[188:191], v[218:221], v[54:57]
	v_mfma_f32_16x16x32_bf16 v[50:53], v[196:199], v[218:221], v[50:53]
	v_mfma_f32_16x16x32_bf16 v[38:41], v[188:191], v[226:229], v[38:41]
	v_mfma_f32_16x16x32_bf16 v[34:37], v[196:199], v[226:229], v[34:37]
	v_mfma_f32_16x16x32_bf16 v[22:25], v[188:191], v[234:237], v[22:25]
	v_mfma_f32_16x16x32_bf16 v[18:21], v[196:199], v[234:237], v[18:21]
	v_mfma_f32_16x16x32_bf16 v[6:9], v[188:191], v[242:245], v[6:9]
	v_mfma_f32_16x16x32_bf16 v[2:5], v[196:199], v[242:245], v[2:5]
	s_barrier
	s_add_i32 s66, s66, 2
	s_add_u32 s86, s86, 0x100
	s_addc_u32 s87, s87, 0
	s_add_u32 s64, s64, 0x100
	s_addc_u32 s65, s65, 0
	s_cmp_gt_u32 s66, 29
	s_cbranch_scc0 .LBB0_708
	s_and_b64 vcc, exec, s[16:17]
	s_cbranch_vccz .LBB0_711
	s_barrier

.LBB0_853:
	s_add_i32 s71, s8, 2
	s_add_u32 s9, s86, 0xffe00080
	s_addc_u32 s72, s87, -1
	s_add_i32 s73, 0, 0x10000
	s_cmp_eq_u32 s68, s8
	s_cselect_b32 s93, s7, s72
	s_cselect_b32 s92, s47, s9
	v_add_u32_e32 v154, s73, v1
	s_cselect_b32 s9, s45, s70
	s_cselect_b32 s8, s67, s69
	s_add_i32 s74, 0, 0x14000
	s_waitcnt lgkmcnt(0)
	ds_read_b128 v[150:153], v154
	ds_read_b128 v[158:161], v154 offset:1024
	ds_read_b128 v[170:173], v154 offset:2048
	ds_read_b128 v[184:187], v154 offset:3072
	v_add_u32_e32 v154, s74, v1
	ds_read_b128 v[188:191], v154
	ds_read_b128 v[192:195], v154 offset:1024
	ds_read_b128 v[196:199], v154 offset:2048
	ds_read_b128 v[214:217], v154 offset:3072
	v_lshl_add_u64 v[154:155], s[86:87], 0, v[146:147]
	s_add_i32 m0, s17, 0xc000
	ds_read_b128 v[218:221], v156
	ds_read_b128 v[222:225], v156 offset:1024
	ds_read_b128 v[226:229], v156 offset:2048
	ds_read_b128 v[230:233], v156 offset:3072
	ds_read_b128 v[234:237], v156 offset:4096
	ds_read_b128 v[238:241], v156 offset:5120
	ds_read_b128 v[242:245], v156 offset:6144
	ds_read_b128 v[246:249], v156 offset:7168
	global_load_lds_dwordx4 v[154:155], off
	v_lshl_add_u64 v[154:155], s[86:87], 0, v[148:149]
	s_add_i32 m0, s17, 0xe000
	s_nop 0
	global_load_lds_dwordx4 v[154:155], off
	s_waitcnt vmcnt(8) lgkmcnt(0)
	s_barrier
	v_mfma_f32_16x16x32_bf16 v[132:135], v[150:153], v[218:221], v[132:135]
	v_mfma_f32_16x16x32_bf16 v[128:131], v[170:173], v[218:221], v[128:131]
	v_mfma_f32_16x16x32_bf16 v[124:127], v[150:153], v[226:229], v[124:127]
	v_mfma_f32_16x16x32_bf16 v[120:123], v[170:173], v[226:229], v[120:123]
	v_mfma_f32_16x16x32_bf16 v[106:109], v[150:153], v[234:237], v[106:109]
	v_mfma_f32_16x16x32_bf16 v[98:101], v[170:173], v[234:237], v[98:101]
	v_mfma_f32_16x16x32_bf16 v[90:93], v[150:153], v[242:245], v[90:93]
	v_mfma_f32_16x16x32_bf16 v[82:85], v[170:173], v[242:245], v[82:85]
	v_mfma_f32_16x16x32_bf16 v[132:135], v[158:161], v[222:225], v[132:135]
	v_mfma_f32_16x16x32_bf16 v[128:131], v[184:187], v[222:225], v[128:131]
	v_mfma_f32_16x16x32_bf16 v[124:127], v[158:161], v[230:233], v[124:127]
	v_mfma_f32_16x16x32_bf16 v[120:123], v[184:187], v[230:233], v[120:123]
	v_mfma_f32_16x16x32_bf16 v[106:109], v[158:161], v[238:241], v[106:109]
	v_mfma_f32_16x16x32_bf16 v[98:101], v[184:187], v[238:241], v[98:101]
	v_mfma_f32_16x16x32_bf16 v[90:93], v[158:161], v[246:249], v[90:93]
	v_mfma_f32_16x16x32_bf16 v[82:85], v[184:187], v[246:249], v[82:85]
	v_mfma_f32_16x16x32_bf16 v[116:119], v[188:191], v[218:221], v[116:119]
	v_mfma_f32_16x16x32_bf16 v[102:105], v[196:199], v[218:221], v[102:105]
	v_mfma_f32_16x16x32_bf16 v[94:97], v[188:191], v[226:229], v[94:97]
	v_mfma_f32_16x16x32_bf16 v[86:89], v[196:199], v[226:229], v[86:89]
	v_mfma_f32_16x16x32_bf16 v[78:81], v[188:191], v[234:237], v[78:81]
	v_mfma_f32_16x16x32_bf16 v[74:77], v[196:199], v[234:237], v[74:77]
	v_mfma_f32_16x16x32_bf16 v[70:73], v[188:191], v[242:245], v[70:73]
	v_mfma_f32_16x16x32_bf16 v[66:69], v[196:199], v[242:245], v[66:69]
	v_mfma_f32_16x16x32_bf16 v[116:119], v[192:195], v[222:225], v[116:119]
	v_mfma_f32_16x16x32_bf16 v[102:105], v[214:217], v[222:225], v[102:105]
	v_mfma_f32_16x16x32_bf16 v[94:97], v[192:195], v[230:233], v[94:97]
	v_mfma_f32_16x16x32_bf16 v[86:89], v[214:217], v[230:233], v[86:89]
	v_mfma_f32_16x16x32_bf16 v[78:81], v[192:195], v[238:241], v[78:81]
	v_mfma_f32_16x16x32_bf16 v[74:77], v[214:217], v[238:241], v[74:77]
	v_mfma_f32_16x16x32_bf16 v[70:73], v[192:195], v[246:249], v[70:73]
	v_mfma_f32_16x16x32_bf16 v[66:69], v[214:217], v[246:249], v[66:69]
	s_barrier
	s_add_i32 s72, s73, s37
	v_lshl_add_u64 v[154:155], s[8:9], 0, v[136:137]
	s_mov_b32 m0, s72
	ds_read_b128 v[218:221], v156 offset:16384
	ds_read_b128 v[222:225], v156 offset:17408
	ds_read_b128 v[226:229], v156 offset:18432
	ds_read_b128 v[230:233], v156 offset:19456
	ds_read_b128 v[234:237], v156 offset:20480
	ds_read_b128 v[238:241], v156 offset:21504
	ds_read_b128 v[242:245], v156 offset:22528
	ds_read_b128 v[246:249], v156 offset:23552
	global_load_lds_dwordx4 v[154:155], off
	s_add_i32 m0, s72, 0x2000
	s_add_u32 s72, s8, 0x200000
	v_lshl_add_u64 v[162:163], s[8:9], 0, v[140:141]
	s_addc_u32 s73, s9, 0
	s_add_i32 s74, s74, s37
	global_load_lds_dwordx4 v[162:163], off
	v_lshl_add_u64 v[200:201], s[72:73], 0, v[136:137]
	s_mov_b32 m0, s74
	v_lshl_add_u64 v[206:207], s[92:93], 0, v[138:139]
	global_load_lds_dwordx4 v[200:201], off
	v_lshl_add_u64 v[200:201], s[72:73], 0, v[140:141]
	s_add_i32 m0, s74, 0x2000
	s_nop 0
	global_load_lds_dwordx4 v[200:201], off
	v_lshl_add_u64 v[200:201], s[92:93], 0, v[110:111]
	s_mov_b32 m0, s17
	s_nop 0
	global_load_lds_dwordx4 v[200:201], off
	s_mov_b32 m0, s57
	s_nop 0
	global_load_lds_dwordx4 v[206:207], off
	s_waitcnt vmcnt(8) lgkmcnt(0)
	s_barrier
	v_mfma_f32_16x16x32_bf16 v[62:65], v[150:153], v[218:221], v[62:65]
	v_mfma_f32_16x16x32_bf16 v[58:61], v[170:173], v[218:221], v[58:61]
	v_mfma_f32_16x16x32_bf16 v[54:57], v[150:153], v[226:229], v[54:57]
	v_mfma_f32_16x16x32_bf16 v[50:53], v[170:173], v[226:229], v[50:53]
	v_mfma_f32_16x16x32_bf16 v[42:45], v[150:153], v[234:237], v[42:45]
	v_mfma_f32_16x16x32_bf16 v[34:37], v[170:173], v[234:237], v[34:37]
	v_mfma_f32_16x16x32_bf16 v[26:29], v[150:153], v[242:245], v[26:29]
	v_mfma_f32_16x16x32_bf16 v[18:21], v[170:173], v[242:245], v[18:21]
	v_mfma_f32_16x16x32_bf16 v[62:65], v[158:161], v[222:225], v[62:65]
	v_mfma_f32_16x16x32_bf16 v[58:61], v[184:187], v[222:225], v[58:61]
	v_mfma_f32_16x16x32_bf16 v[54:57], v[158:161], v[230:233], v[54:57]
	v_mfma_f32_16x16x32_bf16 v[50:53], v[184:187], v[230:233], v[50:53]
	v_mfma_f32_16x16x32_bf16 v[42:45], v[158:161], v[238:241], v[42:45]
	v_mfma_f32_16x16x32_bf16 v[34:37], v[184:187], v[238:241], v[34:37]
	v_mfma_f32_16x16x32_bf16 v[26:29], v[158:161], v[246:249], v[26:29]
	v_mfma_f32_16x16x32_bf16 v[18:21], v[184:187], v[246:249], v[18:21]
	v_mfma_f32_16x16x32_bf16 v[46:49], v[188:191], v[218:221], v[46:49]
	v_mfma_f32_16x16x32_bf16 v[38:41], v[196:199], v[218:221], v[38:41]
	v_mfma_f32_16x16x32_bf16 v[30:33], v[188:191], v[226:229], v[30:33]
	v_mfma_f32_16x16x32_bf16 v[22:25], v[196:199], v[226:229], v[22:25]
	v_mfma_f32_16x16x32_bf16 v[14:17], v[188:191], v[234:237], v[14:17]
	v_mfma_f32_16x16x32_bf16 v[10:13], v[196:199], v[234:237], v[10:13]
	v_mfma_f32_16x16x32_bf16 v[6:9], v[188:191], v[242:245], v[6:9]
	v_mfma_f32_16x16x32_bf16 v[2:5], v[196:199], v[242:245], v[2:5]
	v_mfma_f32_16x16x32_bf16 v[46:49], v[192:195], v[222:225], v[46:49]
	v_mfma_f32_16x16x32_bf16 v[38:41], v[214:217], v[222:225], v[38:41]
	v_mfma_f32_16x16x32_bf16 v[30:33], v[192:195], v[230:233], v[30:33]
	v_mfma_f32_16x16x32_bf16 v[22:25], v[214:217], v[230:233], v[22:25]
	v_mfma_f32_16x16x32_bf16 v[14:17], v[192:195], v[238:241], v[14:17]
	v_mfma_f32_16x16x32_bf16 v[10:13], v[214:217], v[238:241], v[10:13]
	v_mfma_f32_16x16x32_bf16 v[6:9], v[192:195], v[246:249], v[6:9]
	v_mfma_f32_16x16x32_bf16 v[2:5], v[214:217], v[246:249], v[2:5]
	s_barrier
	s_add_i32 s74, 0, 0x18000
	v_add_u32_e32 v157, s74, v1
	s_add_i32 s75, 0, 0x1c000
	ds_read_b128 v[150:153], v157
	ds_read_b128 v[158:161], v157 offset:1024
	ds_read_b128 v[170:173], v157 offset:2048
	ds_read_b128 v[184:187], v157 offset:3072
	v_add_u32_e32 v157, s75, v1
	ds_read_b128 v[188:191], v157
	ds_read_b128 v[192:195], v157 offset:1024
	ds_read_b128 v[196:199], v157 offset:2048
	ds_read_b128 v[214:217], v157 offset:3072
	s_add_u32 s72, s92, 0x200000
	s_addc_u32 s73, s93, 0
	s_mov_b32 m0, s58
	v_lshl_add_u64 v[250:251], s[72:73], 0, v[110:111]
	ds_read_b128 v[218:221], v156 offset:32768
	ds_read_b128 v[222:225], v156 offset:33792
	ds_read_b128 v[226:229], v156 offset:34816
	ds_read_b128 v[230:233], v156 offset:35840
	ds_read_b128 v[234:237], v156 offset:36864
	ds_read_b128 v[238:241], v156 offset:37888
	ds_read_b128 v[242:245], v156 offset:38912
	ds_read_b128 v[246:249], v156 offset:39936
	global_load_lds_dwordx4 v[250:251], off
	v_lshl_add_u64 v[250:251], s[72:73], 0, v[138:139]
	s_mov_b32 m0, s59
	s_nop 0
	global_load_lds_dwordx4 v[250:251], off
	s_waitcnt vmcnt(8) lgkmcnt(0)
	s_barrier
	v_mfma_f32_16x16x32_bf16 v[132:135], v[150:153], v[218:221], v[132:135]
	v_mfma_f32_16x16x32_bf16 v[128:131], v[170:173], v[218:221], v[128:131]
	v_mfma_f32_16x16x32_bf16 v[124:127], v[150:153], v[226:229], v[124:127]
	v_mfma_f32_16x16x32_bf16 v[120:123], v[170:173], v[226:229], v[120:123]
	v_mfma_f32_16x16x32_bf16 v[106:109], v[150:153], v[234:237], v[106:109]
	v_mfma_f32_16x16x32_bf16 v[98:101], v[170:173], v[234:237], v[98:101]
	v_mfma_f32_16x16x32_bf16 v[90:93], v[150:153], v[242:245], v[90:93]
	v_mfma_f32_16x16x32_bf16 v[82:85], v[170:173], v[242:245], v[82:85]
	v_mfma_f32_16x16x32_bf16 v[132:135], v[158:161], v[222:225], v[132:135]
	v_mfma_f32_16x16x32_bf16 v[128:131], v[184:187], v[222:225], v[128:131]
	v_mfma_f32_16x16x32_bf16 v[124:127], v[158:161], v[230:233], v[124:127]
	v_mfma_f32_16x16x32_bf16 v[120:123], v[184:187], v[230:233], v[120:123]
	v_mfma_f32_16x16x32_bf16 v[106:109], v[158:161], v[238:241], v[106:109]
	v_mfma_f32_16x16x32_bf16 v[98:101], v[184:187], v[238:241], v[98:101]
	v_mfma_f32_16x16x32_bf16 v[90:93], v[158:161], v[246:249], v[90:93]
	v_mfma_f32_16x16x32_bf16 v[82:85], v[184:187], v[246:249], v[82:85]
	v_mfma_f32_16x16x32_bf16 v[116:119], v[188:191], v[218:221], v[116:119]
	v_mfma_f32_16x16x32_bf16 v[102:105], v[196:199], v[218:221], v[102:105]
	v_mfma_f32_16x16x32_bf16 v[94:97], v[188:191], v[226:229], v[94:97]
	v_mfma_f32_16x16x32_bf16 v[86:89], v[196:199], v[226:229], v[86:89]
	v_mfma_f32_16x16x32_bf16 v[78:81], v[188:191], v[234:237], v[78:81]
	v_mfma_f32_16x16x32_bf16 v[74:77], v[196:199], v[234:237], v[74:77]
	v_mfma_f32_16x16x32_bf16 v[70:73], v[188:191], v[242:245], v[70:73]
	v_mfma_f32_16x16x32_bf16 v[66:69], v[196:199], v[242:245], v[66:69]
	v_mfma_f32_16x16x32_bf16 v[116:119], v[192:195], v[222:225], v[116:119]
	v_mfma_f32_16x16x32_bf16 v[102:105], v[214:217], v[222:225], v[102:105]
	v_mfma_f32_16x16x32_bf16 v[94:97], v[192:195], v[230:233], v[94:97]
	v_mfma_f32_16x16x32_bf16 v[86:89], v[214:217], v[230:233], v[86:89]
	v_mfma_f32_16x16x32_bf16 v[78:81], v[192:195], v[238:241], v[78:81]
	v_mfma_f32_16x16x32_bf16 v[74:77], v[214:217], v[238:241], v[74:77]
	v_mfma_f32_16x16x32_bf16 v[70:73], v[192:195], v[246:249], v[70:73]
	v_mfma_f32_16x16x32_bf16 v[66:69], v[214:217], v[246:249], v[66:69]
	s_barrier
	s_add_i32 s72, s74, s37
	v_lshl_add_u64 v[154:155], v[154:155], 0, s[26:27]
	s_mov_b32 m0, s72
	ds_read_b128 v[218:221], v156 offset:49152
	ds_read_b128 v[222:225], v156 offset:50176
	ds_read_b128 v[226:229], v156 offset:51200
	ds_read_b128 v[230:233], v156 offset:52224
	ds_read_b128 v[234:237], v156 offset:53248
	ds_read_b128 v[238:241], v156 offset:54272
	ds_read_b128 v[242:245], v156 offset:55296
	ds_read_b128 v[246:249], v156 offset:56320
	global_load_lds_dwordx4 v[154:155], off
	s_add_i32 m0, s72, 0x2000
	s_add_u32 s8, s8, 0x200080
	v_lshl_add_u64 v[154:155], v[162:163], 0, s[26:27]
	s_addc_u32 s9, s9, 0
	s_add_i32 s72, s75, s37
	global_load_lds_dwordx4 v[154:155], off
	v_lshl_add_u64 v[154:155], s[8:9], 0, v[136:137]
	s_mov_b32 m0, s72
	s_nop 0
	global_load_lds_dwordx4 v[154:155], off
	v_lshl_add_u64 v[154:155], s[8:9], 0, v[140:141]
	s_add_i32 m0, s72, 0x2000
	s_nop 0
	global_load_lds_dwordx4 v[154:155], off
	v_lshl_add_u64 v[154:155], v[200:201], 0, s[26:27]
	s_mov_b32 m0, s61
	s_nop 0
	global_load_lds_dwordx4 v[154:155], off
	v_lshl_add_u64 v[154:155], v[206:207], 0, s[26:27]
	s_mov_b32 m0, s62
	s_nop 0
	global_load_lds_dwordx4 v[154:155], off
	s_waitcnt vmcnt(8) lgkmcnt(0)
	s_barrier
	v_mfma_f32_16x16x32_bf16 v[62:65], v[150:153], v[218:221], v[62:65]
	v_mfma_f32_16x16x32_bf16 v[58:61], v[170:173], v[218:221], v[58:61]
	v_mfma_f32_16x16x32_bf16 v[54:57], v[150:153], v[226:229], v[54:57]
	v_mfma_f32_16x16x32_bf16 v[50:53], v[170:173], v[226:229], v[50:53]
	v_mfma_f32_16x16x32_bf16 v[42:45], v[150:153], v[234:237], v[42:45]
	v_mfma_f32_16x16x32_bf16 v[34:37], v[170:173], v[234:237], v[34:37]
	v_mfma_f32_16x16x32_bf16 v[26:29], v[150:153], v[242:245], v[26:29]
	v_mfma_f32_16x16x32_bf16 v[18:21], v[170:173], v[242:245], v[18:21]
	v_mfma_f32_16x16x32_bf16 v[62:65], v[158:161], v[222:225], v[62:65]
	v_mfma_f32_16x16x32_bf16 v[58:61], v[184:187], v[222:225], v[58:61]
	v_mfma_f32_16x16x32_bf16 v[54:57], v[158:161], v[230:233], v[54:57]
	v_mfma_f32_16x16x32_bf16 v[50:53], v[184:187], v[230:233], v[50:53]
	v_mfma_f32_16x16x32_bf16 v[42:45], v[158:161], v[238:241], v[42:45]
	v_mfma_f32_16x16x32_bf16 v[34:37], v[184:187], v[238:241], v[34:37]
	v_mfma_f32_16x16x32_bf16 v[26:29], v[158:161], v[246:249], v[26:29]
	v_mfma_f32_16x16x32_bf16 v[18:21], v[184:187], v[246:249], v[18:21]
	v_mfma_f32_16x16x32_bf16 v[46:49], v[188:191], v[218:221], v[46:49]
	v_mfma_f32_16x16x32_bf16 v[38:41], v[196:199], v[218:221], v[38:41]
	v_mfma_f32_16x16x32_bf16 v[30:33], v[188:191], v[226:229], v[30:33]
	v_mfma_f32_16x16x32_bf16 v[22:25], v[196:199], v[226:229], v[22:25]
	v_mfma_f32_16x16x32_bf16 v[14:17], v[188:191], v[234:237], v[14:17]
	v_mfma_f32_16x16x32_bf16 v[10:13], v[196:199], v[234:237], v[10:13]
	v_mfma_f32_16x16x32_bf16 v[6:9], v[188:191], v[242:245], v[6:9]
	v_mfma_f32_16x16x32_bf16 v[2:5], v[196:199], v[242:245], v[2:5]
	v_mfma_f32_16x16x32_bf16 v[46:49], v[192:195], v[222:225], v[46:49]
	v_mfma_f32_16x16x32_bf16 v[38:41], v[214:217], v[222:225], v[38:41]
	v_mfma_f32_16x16x32_bf16 v[30:33], v[192:195], v[230:233], v[30:33]
	v_mfma_f32_16x16x32_bf16 v[22:25], v[214:217], v[230:233], v[22:25]
	v_mfma_f32_16x16x32_bf16 v[14:17], v[192:195], v[238:241], v[14:17]
	v_mfma_f32_16x16x32_bf16 v[10:13], v[214:217], v[238:241], v[10:13]
	v_mfma_f32_16x16x32_bf16 v[6:9], v[192:195], v[246:249], v[6:9]
	v_mfma_f32_16x16x32_bf16 v[2:5], v[214:217], v[246:249], v[2:5]
	s_barrier
	s_add_u32 s86, s86, 0x100
	s_addc_u32 s87, s87, 0
	s_add_u32 s69, s69, 0x100
	s_addc_u32 s70, s70, 0
	s_cmp_ge_u32 s71, s66
	s_mov_b32 s8, s71
	s_cbranch_scc0 .LBB0_853
	s_and_b64 vcc, exec, s[42:43]
	s_cbranch_vccz .LBB0_856
	s_barrier
